# k18: k15 + grid barrier: the last XCD leader releases every XCD's workgroups directly (one poll-and-relay hop less)
# speedup vs baseline: 1.0213x; 1.0034x over previous
; __device__ __forceinline__ unsigned xb_ld(unsigned* p)              { return __hip_atomic_load(p, __ATOMIC_RELAXED, __HIP_MEMORY_SCOPE_AGENT); }
; __device__ __forceinline__ unsigned xb_add(unsigned* p, unsigned v) { return __hip_atomic_fetch_add(p, v, __ATOMIC_RELAXED, __HIP_MEMORY_SCOPE_AGENT); }
; #define XB_SPIN(cond, bar) do { unsigned _sp = 0; while (cond) { __builtin_amdgcn_s_sleep(1); \
;     if ((++_sp & 255u) == 0u) { if (xb_ld(&(bar)[XB_TMO])) break; if (_sp > XB_SPIN_CAP) { atomicAdd(&(bar)[XB_TMO], 1u); break; } } } } while (0)
; __device__ __forceinline__ void xcd_barrier(const XcdBarrier& b) {
;     ...
;             const unsigned og = xb_add(&bar[XB_TOP], 1u);
;             const unsigned tg = og / nx;
;             if (og + 1u == (tg + 1u) * nx) xb_add(&bar[XB_TOPGEN], 1u);
;             else XB_SPIN(xb_ld(&bar[XB_TOPGEN]) == tg, bar);
.LBB0_133:
	s_or_b64 exec, exec, s[8:9]
	buffer_inv sc1
	v_cvt_f32_u32_e32 v4, v0
	s_waitcnt vmcnt(0)
	v_readfirstlane_b32 s6, v2
	v_sub_u32_e32 v2, 0, v0
	s_mov_b64 s[8:9], -1
	v_rcp_iflag_f32_e32 v4, v4
	v_add_u32_e32 v1, s6, v1
	v_add_u32_e32 v5, 1, v1
	v_readlane_b32 s6, v251, 25
	v_mul_f32_e32 v4, 0x4f7ffffe, v4
	v_cvt_u32_f32_e32 v4, v4
	v_readlane_b32 s7, v251, 26
	v_mul_lo_u32 v2, v2, v4
	v_mul_hi_u32 v2, v4, v2
	v_add_u32_e32 v2, v4, v2
	v_mul_hi_u32 v2, v1, v2
	v_mul_lo_u32 v4, v2, v0
	v_sub_u32_e32 v1, v1, v4
	v_add_u32_e32 v6, 1, v2
	v_sub_u32_e32 v4, v1, v0
	v_cmp_ge_u32_e32 vcc, v1, v0
	s_nop 1
	v_cndmask_b32_e32 v2, v2, v6, vcc
	v_cndmask_b32_e32 v1, v1, v4, vcc
	v_add_u32_e32 v4, 1, v2
	v_cmp_ge_u32_e32 vcc, v1, v0
	s_nop 1
	v_cndmask_b32_e32 v2, v2, v4, vcc
	v_mul_lo_u32 v1, v0, v2
	v_add_u32_e32 v0, v1, v0
	v_cmp_ne_u32_e32 vcc, v5, v0
	v_mov_b64_e32 v[0:1], s[6:7]
	s_mov_b64 s[98:99], vcc
	s_and_saveexec_b64 s[6:7], vcc
	s_cbranch_execz .LBB0_146
	v_readlane_b32 s8, v251, 25
	v_readlane_b32 s9, v251, 26
	s_mov_b64 s[10:11], 0
	s_nop 3
	global_load_dword v0, v3, s[8:9] sc1
	s_waitcnt vmcnt(0)
	v_cmp_eq_u32_e32 vcc, v0, v2
	s_and_saveexec_b64 s[8:9], vcc
	s_cbranch_execz .LBB0_145
	s_mov_b32 s24, 1
	s_branch .LBB0_137

; __device__ __forceinline__ unsigned xb_ld(unsigned* p)              { return __hip_atomic_load(p, __ATOMIC_RELAXED, __HIP_MEMORY_SCOPE_AGENT); }
; __device__ __forceinline__ unsigned xb_add(unsigned* p, unsigned v) { return __hip_atomic_fetch_add(p, v, __ATOMIC_RELAXED, __HIP_MEMORY_SCOPE_AGENT); }
; #define XB_SPIN(cond, bar) do { unsigned _sp = 0; while (cond) { __builtin_amdgcn_s_sleep(1); \
;     if ((++_sp & 255u) == 0u) { if (xb_ld(&(bar)[XB_TMO])) break; if (_sp > XB_SPIN_CAP) { atomicAdd(&(bar)[XB_TMO], 1u); break; } } } } while (0)
; __device__ __forceinline__ void xcd_barrier(const XcdBarrier& b) {
;     ...
;             if (og + 1u == (tg + 1u) * nx) xb_add(&bar[XB_TOPGEN], 1u);
;             else XB_SPIN(xb_ld(&bar[XB_TOPGEN]) == tg, bar);
;             __builtin_amdgcn_fence(__ATOMIC_ACQUIRE, "agent");
;             xb_add(&bar[XB_XGEN(b.x)], 1u);
;             asm volatile("s_waitcnt vmcnt(0)" ::: "memory");
.LBB0_148:
	s_or_b64 exec, exec, s[6:7]
	s_mov_b64 s[6:7], exec
	v_mbcnt_lo_u32_b32 v0, s6, 0
	v_mbcnt_hi_u32_b32 v0, s7, v0
	v_cmp_eq_u32_e32 vcc, 0, v0
	s_and_saveexec_b64 s[8:9], vcc
	s_cbranch_execz .LBB0_150
	s_and_b64 vcc, s[98:99], exec
	s_cbranch_vccnz .LBB0_150
	s_getreg_b32 s6, hwreg(HW_REG_XCC_ID, 0, 4)
	s_nop 0
	s_and_b32 s6, s6, 15
	s_lshl_b32 s6, s6, 8
	v_subrev_u32_e32 v0, s6, v209
	global_atomic_add v0, v210, s[4:5] offset:1024
	v_add_u32_e32 v0, 0x100, v0
	global_atomic_add v0, v210, s[4:5] offset:1024
	v_add_u32_e32 v0, 0x100, v0
	global_atomic_add v0, v210, s[4:5] offset:1024
	v_add_u32_e32 v0, 0x100, v0
	global_atomic_add v0, v210, s[4:5] offset:1024
	v_add_u32_e32 v0, 0x100, v0
	global_atomic_add v0, v210, s[4:5] offset:1024
	v_add_u32_e32 v0, 0x100, v0
	global_atomic_add v0, v210, s[4:5] offset:1024
	v_add_u32_e32 v0, 0x100, v0
	global_atomic_add v0, v210, s[4:5] offset:1024
	v_add_u32_e32 v0, 0x100, v0
	global_atomic_add v0, v210, s[4:5] offset:1024
	v_add_u32_e32 v0, 0x100, v0
	global_atomic_add v0, v210, s[4:5] offset:1024
	v_add_u32_e32 v0, 0x100, v0
	global_atomic_add v0, v210, s[4:5] offset:1024
	v_add_u32_e32 v0, 0x100, v0
	global_atomic_add v0, v210, s[4:5] offset:1024
	v_add_u32_e32 v0, 0x100, v0
	global_atomic_add v0, v210, s[4:5] offset:1024
	v_add_u32_e32 v0, 0x100, v0
	global_atomic_add v0, v210, s[4:5] offset:1024
	v_add_u32_e32 v0, 0x100, v0
	global_atomic_add v0, v210, s[4:5] offset:1024
	v_add_u32_e32 v0, 0x100, v0
	global_atomic_add v0, v210, s[4:5] offset:1024
	v_add_u32_e32 v0, 0x100, v0
	global_atomic_add v0, v210, s[4:5] offset:1024

; __device__ __forceinline__ unsigned xb_ld(unsigned* p)              { return __hip_atomic_load(p, __ATOMIC_RELAXED, __HIP_MEMORY_SCOPE_AGENT); }
; __device__ __forceinline__ unsigned xb_add(unsigned* p, unsigned v) { return __hip_atomic_fetch_add(p, v, __ATOMIC_RELAXED, __HIP_MEMORY_SCOPE_AGENT); }
; #define XB_SPIN(cond, bar) do { unsigned _sp = 0; while (cond) { __builtin_amdgcn_s_sleep(1); \
;     if ((++_sp & 255u) == 0u) { if (xb_ld(&(bar)[XB_TMO])) break; if (_sp > XB_SPIN_CAP) { atomicAdd(&(bar)[XB_TMO], 1u); break; } } } } while (0)
; __device__ __forceinline__ void xcd_barrier(const XcdBarrier& b) {
;     ...
;             const unsigned og = xb_add(&bar[XB_TOP], 1u);
;             const unsigned tg = og / nx;
;             if (og + 1u == (tg + 1u) * nx) xb_add(&bar[XB_TOPGEN], 1u);
;             else XB_SPIN(xb_ld(&bar[XB_TOPGEN]) == tg, bar);
.LBB0_189:
	s_or_b64 exec, exec, s[8:9]
	buffer_inv sc1
	v_cvt_f32_u32_e32 v4, v0
	s_waitcnt vmcnt(0)
	v_readfirstlane_b32 s6, v2
	v_sub_u32_e32 v2, 0, v0
	s_mov_b64 s[8:9], -1
	v_rcp_iflag_f32_e32 v4, v4
	v_add_u32_e32 v1, s6, v1
	v_add_u32_e32 v5, 1, v1
	v_readlane_b32 s6, v251, 50
	v_mul_f32_e32 v4, 0x4f7ffffe, v4
	v_cvt_u32_f32_e32 v4, v4
	v_readlane_b32 s7, v251, 51
	v_mul_lo_u32 v2, v2, v4
	v_mul_hi_u32 v2, v4, v2
	v_add_u32_e32 v2, v4, v2
	v_mul_hi_u32 v2, v1, v2
	v_mul_lo_u32 v4, v2, v0
	v_sub_u32_e32 v1, v1, v4
	v_add_u32_e32 v6, 1, v2
	v_sub_u32_e32 v4, v1, v0
	v_cmp_ge_u32_e32 vcc, v1, v0
	s_nop 1
	v_cndmask_b32_e32 v2, v2, v6, vcc
	v_cndmask_b32_e32 v1, v1, v4, vcc
	v_add_u32_e32 v4, 1, v2
	v_cmp_ge_u32_e32 vcc, v1, v0
	s_nop 1
	v_cndmask_b32_e32 v2, v2, v4, vcc
	v_mul_lo_u32 v1, v0, v2
	v_add_u32_e32 v0, v1, v0
	v_cmp_ne_u32_e32 vcc, v5, v0
	v_mov_b64_e32 v[0:1], s[6:7]
	s_mov_b64 s[98:99], vcc
	s_and_saveexec_b64 s[6:7], vcc
	s_cbranch_execz .LBB0_201
	v_readlane_b32 s8, v251, 50
	v_readlane_b32 s9, v251, 51
	s_mov_b64 s[10:11], 0
	s_nop 3
	global_load_dword v0, v3, s[8:9] sc1
	s_waitcnt vmcnt(0)
	v_cmp_eq_u32_e32 vcc, v0, v2
	s_and_saveexec_b64 s[8:9], vcc
	s_cbranch_execz .LBB0_200
	s_mov_b32 s24, 1
	s_branch .LBB0_193
